# forgetting-attention loop role A: V staging store moved from the burst between PV and QK into the first QK MFMA gap
# baseline (speedup 1.0000x reference)
; __device__ __forceinline__ s16x4 vtr(ldsp p) { return __builtin_bit_cast(s16x4, __builtin_amdgcn_ds_read_tr16_b64_v4i16((LAS v4i16_t*)p)); }
; #define MASK_BLOCK() do { if (kt == 0 || kt >= diag0) { \
;             _Pragma("unroll") for (int r = 0; r < 16; ++r) { const int kpp = 64 * kt + crow(r, hi); \
;                 if (kpp < 48 || kpp > q_pp) s0[r] = -INFINITY; \
;                 if (kpp + 32 < 48 || kpp + 32 > q_pp) s1[r] = -INFINITY; } } } while (0)
; #define EXPSUM_BLOCK() do { psa = 0.f; psb = 0.f; \
;             _Pragma("unroll") for (int r = 0; r < 16; ++r) { s0[r] = __builtin_amdgcn_exp2f(s0[r]); s1[r] = __builtin_amdgcn_exp2f(s1[r]); psa += s0[r]; asm("" : "+v"(psa)); psb += s1[r]; asm("" : "+v"(psb)); } } while (0)
; template <bool DIFF>
; __device__ __forceinline__ void attn_unit(const AttnP& A, int b, int h, int qi, ldsp lds) {
;     ...
;     for (int kt = kt0; kt < nt; ++kt) {
;         if (kt + 1 < nt) LOAD_TILE(kt + 1);
;         if (64 * kt <= qmax_w) {
;             ldsp Kb = lds + (kt & 1) * STAGE; ldsp Vb = Kb + 64 * KP;
;             bf16x8 kf[8]; bf16x8 ka0, ka1, qa; f32x16 s0, s1;
;     ...
;             QK_BLOCK();
;             s16x4 vlo[8], vhi[8];
; #pragma unroll
;             for (int t = 0; t < 2; ++t)
; #pragma unroll
;                 for (int j = 0; j < 4; ++j) { vlo[t * 4 + j] = vtr(Vb + trb + (16 * j) * VP + t * 64); vhi[t * 4 + j] = vtr(Vb + trb + (16 * j + 8) * VP + t * 64); }
;             __builtin_amdgcn_sched_barrier(0);
;             MASK_BLOCK();
;             bool full = (kt == kt0);
;             float psa, psb;
;             if (!full) {
;                 EXPSUM_BLOCK();
;                 if (__any(psa + psb > 1.0e18f)) { full = true; QK_BLOCK();
.Lfa_s_top:
	s_bitcmp1_b32 s99, 0
	s_cselect_b32 s74, 0x5500, 0
	s_sub_i32 s75, 0x5500, s74
	v_add_u32_e32 v169, s74, v150
	v_add_u32_e32 v0, s74, v164
	v_add_u32_e32 v168, s75, v161
	ds_read_b64_tr_b16 v[106:107], v168 offset:9216
	ds_read_b64_tr_b16 v[108:109], v168 offset:10752
	ds_read_b64_tr_b16 v[110:111], v168 offset:9280
	ds_read_b64_tr_b16 v[112:113], v168 offset:10816
	ds_read_b64_tr_b16 v[116:117], v168 offset:12288
	ds_read_b64_tr_b16 v[118:119], v168 offset:13824
	ds_read_b64_tr_b16 v[120:121], v168 offset:12352
	ds_read_b64_tr_b16 v[122:123], v168 offset:13888
	ds_read_b64_tr_b16 v[124:125], v168 offset:15360
	ds_read_b64_tr_b16 v[126:127], v168 offset:16896
	ds_read_b64_tr_b16 v[128:129], v168 offset:15424
	ds_read_b64_tr_b16 v[130:131], v168 offset:16960
	ds_read_b64_tr_b16 v[132:133], v168 offset:18432
	ds_read_b64_tr_b16 v[134:135], v168 offset:19968
	ds_read_b64_tr_b16 v[136:137], v168 offset:18496
	ds_read_b64_tr_b16 v[138:139], v168 offset:20032
	v_mov_b32_e32 v248, s97
	ds_read_b32 v248, v248
	ds_read_b128 v[170:173], v169
	ds_read_b128 v[244:247], v169 offset:4608
	s_waitcnt lgkmcnt(15)
	v_mfma_f32_32x32x16_bf16 v[18:33], v[106:109], v[66:69], v[18:33]
	ds_read_b128 v[106:109], v169 offset:32
	s_waitcnt lgkmcnt(15)
	v_mfma_f32_32x32x16_bf16 v[2:17], v[110:113], v[66:69], v[2:17]
	ds_read_b128 v[110:113], v169 offset:4640
	s_waitcnt lgkmcnt(15)
	v_mfma_f32_32x32x16_bf16 v[18:33], v[116:119], v[70:73], v[18:33]
	ds_read_b128 v[116:119], v169 offset:64
	s_waitcnt lgkmcnt(14)
	v_mfma_f32_32x32x16_bf16 v[2:17], v[120:123], v[70:73], v[2:17]
	ds_read_b128 v[120:123], v169 offset:4672
	s_waitcnt lgkmcnt(13)
	v_mfma_f32_32x32x16_bf16 v[18:33], v[124:127], v[50:53], v[18:33]
	ds_read_b128 v[124:127], v169 offset:96
	s_waitcnt lgkmcnt(12)
	v_mfma_f32_32x32x16_bf16 v[2:17], v[128:131], v[50:53], v[2:17]
	ds_read_b128 v[128:131], v169 offset:4704
	s_waitcnt lgkmcnt(11)
	v_mfma_f32_32x32x16_bf16 v[18:33], v[132:135], v[54:57], v[18:33]
	ds_read_b128 v[132:135], v0 offset:128
	s_waitcnt lgkmcnt(10)
	v_mfma_f32_32x32x16_bf16 v[2:17], v[136:139], v[54:57], v[2:17]
	ds_read_b128 v[136:139], v0 offset:4736
	s_waitcnt vmcnt(0)
	v_add_u32_e32 v115, s75, v156
	ds_write_b128 v115, v[98:101]
	s_and_saveexec_b64 s[0:1], s[44:45]
	v_xor_b32_e32 v0, 0x80000000, v155
	v_cvt_pk_bf16_f32 v0, v0, 0
	v_lshlrev_b32_e32 v249, 16, v0
	v_sub_f32_e64 v249, -v155, v249
	v_cvt_pk_bf16_f32 v162, v249, 0
	v_lshlrev_b32_e32 v162, 16, v162
	v_sub_f32_e32 v249, v249, v162
	v_cvt_pk_bf16_f32 v249, v249, 0
	v_and_or_b32 v98, v0, s83, v162
	v_and_or_b32 v99, v249, s83, 1.0
	v_mov_b32_e32 v100, v114
	v_mov_b32_e32 v101, v1
	v_add_u32_e32 v0, s75, v159
	ds_write_b128 v0, v[98:101] offset:128
	s_mov_b64 exec, s[0:1]
	s_waitcnt lgkmcnt(11)
	v_mfma_f32_32x32x16_bf16 v[66:81], v[170:173], v[90:93], v[34:49]
	v_add_u32_e32 v115, s74, v158
	ds_write_b128 v115, v[102:105] offset:9216
	s_waitcnt lgkmcnt(11)
	v_mfma_f32_32x32x16_bf16 v[50:65], v[244:247], v[90:93], v[34:49]
	v_sub_f32_e32 v249, v160, v248
	v_cvt_pk_bf16_f32 v162, v249, 0
	v_lshlrev_b32_e32 v162, 16, v162
	s_waitcnt lgkmcnt(10)
	v_mfma_f32_32x32x16_bf16 v[66:81], v[106:109], v[82:85], v[66:81]
	s_waitcnt lgkmcnt(9)
	v_mfma_f32_32x32x16_bf16 v[50:65], v[110:113], v[82:85], v[50:65]
	v_sub_f32_e32 v249, v249, v162
	v_cvt_pk_bf16_f32 v163, v249, 0
	v_and_b32_e32 v157, 0xffff, v163
	v_lshlrev_b32_e32 v163, 16, v163
	s_waitcnt lgkmcnt(8)
	v_mfma_f32_32x32x16_bf16 v[66:81], v[116:119], v[86:89], v[66:81]
	s_waitcnt lgkmcnt(7)
	v_mfma_f32_32x32x16_bf16 v[50:65], v[120:123], v[86:89], v[50:65]
	v_sub_f32_e32 v249, v249, v163
	v_cvt_pk_bf16_f32 v249, v249, 0
	v_or_b32_e32 v162, 0x3f80, v162
	v_lshl_or_b32 v249, v249, 16, v157
	v_cndmask_b32_e64 v140, 0, v114, s[46:47]
	v_cndmask_b32_e64 v142, 0, v249, s[46:47]
	v_cndmask_b32_e64 v141, 0, v162, s[46:47]
	v_mov_b32_e32 v143, v1
	s_waitcnt lgkmcnt(6)
	v_mfma_f32_32x32x16_bf16 v[66:81], v[124:127], v[94:97], v[66:81]
	s_waitcnt lgkmcnt(5)
	v_mfma_f32_32x32x16_bf16 v[50:65], v[128:131], v[94:97], v[50:65]
	s_waitcnt lgkmcnt(4)
	v_mfma_f32_32x32x16_bf16 v[66:81], v[132:135], v[140:143], v[66:81]
	s_waitcnt lgkmcnt(3)
	v_mfma_f32_32x32x16_bf16 v[50:65], v[136:139], v[140:143], v[50:65]
	global_load_dwordx4 v[102:105], v[250:251], off
	v_lshl_add_u64 v[250:251], v[250:251], 0, s[26:27]
	global_load_dwordx4 v[98:101], v[152:153], off
	v_lshl_add_u64 v[152:153], v[152:153], 0, s[26:27]
	s_and_saveexec_b64 s[0:1], s[44:45]
	global_load_dword v155, v[252:253], off
	s_mov_b64 exec, s[0:1]
	s_mov_b64 s[0:1], 0x800
	v_lshl_add_u64 v[252:253], v[252:253], 0, s[0:1]
	s_nop 1
	v_exp_f32_e32 v106, v66
	v_exp_f32_e32 v124, v50
	v_exp_f32_e32 v107, v67
	v_exp_f32_e32 v125, v51
	v_add_f32_e32 v166, 0, v106
	v_add_f32_e32 v167, 0, v124
	v_exp_f32_e32 v108, v68
	v_exp_f32_e32 v126, v52
	v_add_f32_e32 v166, v107, v166
	v_add_f32_e32 v167, v125, v167
	v_exp_f32_e32 v109, v69
	v_exp_f32_e32 v127, v53
	v_add_f32_e32 v166, v108, v166
	v_add_f32_e32 v167, v126, v167
	v_exp_f32_e32 v110, v70
	v_exp_f32_e32 v128, v54
	v_add_f32_e32 v166, v109, v166
	v_add_f32_e32 v167, v127, v167
	v_exp_f32_e32 v111, v71
	v_exp_f32_e32 v129, v55
	v_add_f32_e32 v166, v110, v166
	v_add_f32_e32 v167, v128, v167
	v_exp_f32_e32 v112, v72
	v_exp_f32_e32 v130, v56
	v_add_f32_e32 v166, v111, v166
	v_add_f32_e32 v167, v129, v167
	v_exp_f32_e32 v113, v73
	v_exp_f32_e32 v131, v57
	v_add_f32_e32 v166, v112, v166
	v_add_f32_e32 v167, v130, v167
	v_exp_f32_e32 v116, v74
	v_exp_f32_e32 v132, v58
	v_add_f32_e32 v166, v113, v166
	v_add_f32_e32 v167, v131, v167
	v_exp_f32_e32 v117, v75
	v_exp_f32_e32 v133, v59
	v_add_f32_e32 v166, v116, v166
	v_add_f32_e32 v167, v132, v167
	v_exp_f32_e32 v118, v76
	v_exp_f32_e32 v134, v60
	v_add_f32_e32 v166, v117, v166
	v_add_f32_e32 v167, v133, v167
	v_exp_f32_e32 v119, v77
	v_exp_f32_e32 v135, v61
	v_add_f32_e32 v166, v118, v166
	v_add_f32_e32 v167, v134, v167
	v_exp_f32_e32 v120, v78
	v_exp_f32_e32 v136, v62
	v_add_f32_e32 v166, v119, v166
	v_add_f32_e32 v167, v135, v167
	v_exp_f32_e32 v121, v79
	v_exp_f32_e32 v137, v63
	v_add_f32_e32 v166, v120, v166
	v_add_f32_e32 v167, v136, v167
	v_exp_f32_e32 v122, v80
	v_exp_f32_e32 v138, v64
	v_add_f32_e32 v166, v121, v166
	v_add_f32_e32 v167, v137, v167
	v_exp_f32_e32 v123, v81
	v_exp_f32_e32 v139, v65
	v_add_f32_e32 v166, v122, v166
	v_add_f32_e32 v167, v138, v167
	s_nop 0
	v_add_f32_e32 v166, v123, v166
	v_add_f32_e32 v167, v139, v167
	v_add_f32_e32 v141, v166, v167
	v_cmp_lt_f32_e32 vcc, s85, v141
	s_cbranch_vccnz .Lfa_s_slow
; __device__ __forceinline__ s16x4 vtr(ldsp p) { return __builtin_bit_cast(s16x4, __builtin_amdgcn_ds_read_tr16_b64_v4i16((LAS v4i16_t*)p)); }
; template <bool DIFF>
; __device__ __forceinline__ void attn_unit(const AttnP& A, int b, int h, int qi, ldsp lds) {
;     ...
;             l_run += psa + psb;
;     ...
;             bf16x8 pw[4];
; #pragma unroll
;             for (int j = 0; j < 4; ++j) {
;                 u32x4 pk;
;                 if (j < 2) { const int rb = 8 * (j & 1); pk.x = cvtpk(s0[rb], s0[rb + 1]); pk.y = cvtpk(s0[rb + 2], s0[rb + 3]); pk.z = cvtpk(s0[rb + 4], s0[rb + 5]); pk.w = cvtpk(s0[rb + 6], s0[rb + 7]); }
;                 else { const int rb = 8 * (j & 1); pk.x = cvtpk(s1[rb], s1[rb + 1]); pk.y = cvtpk(s1[rb + 2], s1[rb + 3]); pk.z = cvtpk(s1[rb + 4], s1[rb + 5]); pk.w = cvtpk(s1[rb + 6], s1[rb + 7]); }
;                 pw[j] = __builtin_bit_cast(bf16x8, pk);
;             }
;             __builtin_amdgcn_sched_barrier(0);
;             __builtin_amdgcn_s_setprio(1);
; #pragma unroll
;             for (int t = 0; t < 2; ++t)
; #pragma unroll
;                 for (int j = 0; j < 4; ++j) {
;                     const bf16x8 vf = (bf16x8){vlo[t * 4 + j][0], vlo[t * 4 + j][1], vlo[t * 4 + j][2], vlo[t * 4 + j][3], vhi[t * 4 + j][0], vhi[t * 4 + j][1], vhi[t * 4 + j][2], vhi[t * 4 + j][3]};
;                     o[t] = __builtin_amdgcn_mfma_f32_32x32x16_bf16(vf, pw[j], o[t], 0, 0, 0);
;                 }
;             if (DIFF) {
; #pragma unroll
;                 for (int t = 2; t < NTD; ++t)
; #pragma unroll
;                     for (int j = 0; j < 4; ++j) { vlo[(t - 2) * 4 + j] = vtr(Vb + trb + (16 * j) * VP + t * 64); vhi[(t - 2) * 4 + j] = vtr(Vb + trb + (16 * j + 8) * VP + t * 64); }
;                 __builtin_amdgcn_sched_barrier(0);
; #pragma unroll
;                 for (int t = 2; t < NTD; ++t)
; #pragma unroll
;                     for (int j = 0; j < 4; ++j) {
;                         const int i = (t - 2) * 4 + j;
;                         const bf16x8 vf = (bf16x8){vlo[i][0], vlo[i][1], vlo[i][2], vlo[i][3], vhi[i][0], vhi[i][1], vhi[i][2], vhi[i][3]};
;                         o[t] = __builtin_amdgcn_mfma_f32_32x32x16_bf16(vf, pw[j], o[t], 0, 0, 0);
;                     }
;             }
;             __builtin_amdgcn_s_setprio(0);
;         }
;         if (kt + 1 < nt) STORE_TILE((kt + 1) & 1);
;         __syncthreads();
;     }
	v_cvt_pk_bf16_f32 v66, v106, v107
	v_cvt_pk_bf16_f32 v67, v108, v109
	v_cvt_pk_bf16_f32 v68, v110, v111
	v_cvt_pk_bf16_f32 v69, v112, v113
	v_cvt_pk_bf16_f32 v70, v116, v117
	v_cvt_pk_bf16_f32 v71, v118, v119
	v_cvt_pk_bf16_f32 v72, v120, v121
	v_cvt_pk_bf16_f32 v73, v122, v123
	v_cvt_pk_bf16_f32 v50, v124, v125
	v_cvt_pk_bf16_f32 v51, v126, v127
	v_cvt_pk_bf16_f32 v52, v128, v129
	v_cvt_pk_bf16_f32 v53, v130, v131
	v_cvt_pk_bf16_f32 v54, v132, v133
	v_cvt_pk_bf16_f32 v55, v134, v135
	v_cvt_pk_bf16_f32 v56, v136, v137
	v_cvt_pk_bf16_f32 v57, v138, v139
	v_add_f32_e32 v154, v141, v154
	s_waitcnt lgkmcnt(0)
	s_barrier
	s_add_i32 s99, s99, 1
	s_add_i32 s94, s94, 1
	s_add_i32 s97, s97, 4
	s_add_i32 s98, s98, 64
	s_add_i32 s0, s95, -1
	s_cmp_le_i32 s99, s0
	s_cbranch_scc1 .Lfa_s_top
